# weights first used in phase 9+ (2560 of 11664 tiles) are transposed in the idle tail of phase 2 (168 workgroups without a twelfth GEMM unit) instead of phase 0
# speedup vs baseline: 1.0089x; 1.0089x over previous
; __device__ __forceinline__ void phase0(const Params& P, unsigned char* smem) {
;     ...
;     auto lookup = [&](int it, TItem& t, int& N) {
;         int r = it < total ? it : total - 1;
;         t.src = nullptr; t.dst = nullptr; t.K = 0; t.mode = 0; t.n0 = 0; N = 0;
; #pragma unroll
;         for (int i = 0; i < 11; ++i) {
;             const int cnt = (tw[i].K >> 6) * (tw[i].N >> 5);
;             if (r >= 0 && r < cnt) {
;                 const int nblk = tw[i].N >> 5, kb = r / nblk, nb = r - kb * nblk, k0 = kb * 64, n0 = nb * 32, tid = threadIdx.x & 255;
;                 N = tw[i].N; t.K = tw[i].K; t.mode = tw[i].mode; t.n0 = n0;
;                 t.src = P.in[tw[i].in] + (size_t)(k0 + (tid >> 5)) * tw[i].N + n0 + (tid & 31);
;                 t.dst = (bf16_t*)(P.ws + tw[i].off) + k0 + (tid & 7) * 8;
;             }
;             r -= cnt;
;         }
;     };
.Ltr_ic:
	s_mov_b32 s1, s0
	s_mov_b32 s2, 0
	s_cmpk_lt_u32 s1, 0x1b80
	s_cselect_b32 s19, 0, 0x580
	s_add_u32 s19, s19, s1
	s_cmpk_lt_u32 s19, 0x580
	s_cbranch_scc1 .Ltr1_m0
	s_cmpk_lt_u32 s19, 0xb00
	s_cbranch_scc1 .Ltr1_m1
	s_cmpk_lt_u32 s19, 0x1080
	s_cbranch_scc1 .Ltr1_m2
	s_cmpk_lt_u32 s19, 0x1600
	s_cbranch_scc1 .Ltr1_m3
	s_cmpk_lt_u32 s19, 0x1b80
	s_cbranch_scc1 .Ltr1_m4
	s_cmpk_lt_u32 s19, 0x2100
	s_cbranch_scc1 .Ltr1_m5
	s_cmpk_lt_u32 s19, 0x2910
	s_cbranch_scc1 .Ltr1_m6
	s_cmpk_lt_u32 s19, 0x2990
	s_cbranch_scc1 .Ltr1_m7
	s_cmpk_lt_u32 s19, 0x2a90
	s_cbranch_scc1 .Ltr1_m8
	s_cmpk_lt_u32 s19, 0x2b90
	s_cbranch_scc1 .Ltr1_m9
	s_sub_u32 s3, s19, 0x2b90
	v_readlane_b32 s6, v251, 43
	v_readlane_b32 s7, v251, 44
	s_mov_b32 s13, 0x2c00000
	s_mov_b32 s14, 0
	s_branch .Ltr1_c1024_1024
.Ltr1_m9:
	s_sub_u32 s3, s19, 0x2a90
	v_readlane_b32 s6, v251, 41
	v_readlane_b32 s7, v251, 42
	s_mov_b32 s13, 0x2b00000
	s_mov_b32 s14, 0
	s_branch .Ltr1_c512_1024
.Ltr1_m8:
	s_sub_u32 s3, s19, 0x2990
	v_readlane_b32 s6, v251, 33
	v_readlane_b32 s7, v251, 34
	s_mov_b32 s13, 0x2a00000
	s_mov_b32 s14, 0
	s_branch .Ltr1_c512_1024
.Ltr1_m7:
	s_sub_u32 s3, s19, 0x2910
	v_readlane_b32 s6, v251, 29
	v_readlane_b32 s7, v251, 30
	s_mov_b32 s13, 0x2980000
	s_mov_b32 s14, 0
	s_branch .Ltr1_c512_512
.Ltr1_m6:
	s_sub_u32 s3, s19, 0x2100
	v_readlane_b32 s6, v251, 11
	v_readlane_b32 s7, v251, 12
	s_mov_b32 s13, 0x2100000
	s_mov_b32 s14, 3
	s_branch .Ltr1_c1024_4128
.Ltr1_m5:
	s_sub_u32 s3, s19, 0x1b80
	v_readlane_b32 s6, v251, 51
	v_readlane_b32 s7, v251, 52
	s_mov_b32 s13, 0x1b80000
	s_mov_b32 s14, 0
	s_branch .Ltr1_c2816_1024
.Ltr1_m4:
	s_sub_u32 s3, s19, 0x1600
	v_readlane_b32 s6, v251, 49
	v_readlane_b32 s7, v251, 50
	s_mov_b32 s13, 0x1080000
	s_mov_b32 s14, 2
	s_branch .Ltr1_c1024_2816
.Ltr1_m3:
	s_sub_u32 s3, s19, 0x1080
	v_readlane_b32 s6, v251, 47
	v_readlane_b32 s7, v251, 48
	s_mov_b32 s13, 0x1080000
	s_mov_b32 s14, 1
	s_branch .Ltr1_c1024_2816
.Ltr1_m2:
	s_sub_u32 s3, s19, 0xb00
	v_readlane_b32 s6, v251, 7
	v_readlane_b32 s7, v251, 8
	s_mov_b32 s13, 0xb00000
	s_mov_b32 s14, 0
	s_branch .Ltr1_c2816_1024
.Ltr1_m1:
	s_sub_u32 s3, s19, 0x580
	v_readlane_b32 s6, v251, 5
	v_readlane_b32 s7, v251, 6
	s_mov_b32 s13, 0x0
	s_mov_b32 s14, 2
	s_branch .Ltr1_c1024_2816
.Ltr1_m0:
	s_mov_b32 s3, s19
	s_mov_b64 s[6:7], s[50:51]
	s_mov_b32 s13, 0x0
	s_mov_b32 s14, 1
	s_branch .Ltr1_c1024_2816

; __device__ __forceinline__ void phase0(const Params& P, unsigned char* smem) {
;     ...
;     auto lookup = [&](int it, TItem& t, int& N) {
;         int r = it < total ? it : total - 1;
;         t.src = nullptr; t.dst = nullptr; t.K = 0; t.mode = 0; t.n0 = 0; N = 0;
; #pragma unroll
;         for (int i = 0; i < 11; ++i) {
;             const int cnt = (tw[i].K >> 6) * (tw[i].N >> 5);
;             if (r >= 0 && r < cnt) {
;                 const int nblk = tw[i].N >> 5, kb = r / nblk, nb = r - kb * nblk, k0 = kb * 64, n0 = nb * 32, tid = threadIdx.x & 255;
;                 N = tw[i].N; t.K = tw[i].K; t.mode = tw[i].mode; t.n0 = n0;
;                 t.src = P.in[tw[i].in] + (size_t)(k0 + (tid >> 5)) * tw[i].N + n0 + (tid & 31);
;                 t.dst = (bf16_t*)(P.ws + tw[i].off) + k0 + (tid & 7) * 8;
;             }
;             r -= cnt;
;         }
;     };
.Ltr2_chk:
	s_cmpk_lt_u32 s1, 0x2390
	s_cbranch_scc0 .Ltr_last0f
	s_cmpk_lt_u32 s1, 0x1b80
	s_cselect_b32 s19, 0, 0x580
	s_add_u32 s19, s19, s1
	s_cmpk_lt_u32 s19, 0x580
	s_cbranch_scc1 .Ltr3_m0
	s_cmpk_lt_u32 s19, 0xb00
	s_cbranch_scc1 .Ltr3_m1
	s_cmpk_lt_u32 s19, 0x1080
	s_cbranch_scc1 .Ltr3_m2
	s_cmpk_lt_u32 s19, 0x1600
	s_cbranch_scc1 .Ltr3_m3
	s_cmpk_lt_u32 s19, 0x1b80
	s_cbranch_scc1 .Ltr3_m4
	s_cmpk_lt_u32 s19, 0x2100
	s_cbranch_scc1 .Ltr3_m5
	s_cmpk_lt_u32 s19, 0x2910
	s_cbranch_scc1 .Ltr3_m6
	s_cmpk_lt_u32 s19, 0x2990
	s_cbranch_scc1 .Ltr3_m7
	s_cmpk_lt_u32 s19, 0x2a90
	s_cbranch_scc1 .Ltr3_m8
	s_cmpk_lt_u32 s19, 0x2b90
	s_cbranch_scc1 .Ltr3_m9
	s_sub_u32 s3, s19, 0x2b90
	v_readlane_b32 s6, v251, 43
	v_readlane_b32 s7, v251, 44
	s_mov_b32 s13, 0x2c00000
	s_mov_b32 s14, 0
	s_branch .Ltr3_c1024_1024

; __device__ __forceinline__ void phase0(const Params& P, unsigned char* smem) {
;     ...
;     auto lookup = [&](int it, TItem& t, int& N) {
;         int r = it < total ? it : total - 1;
;         t.src = nullptr; t.dst = nullptr; t.K = 0; t.mode = 0; t.n0 = 0; N = 0;
; #pragma unroll
;         for (int i = 0; i < 11; ++i) {
;             const int cnt = (tw[i].K >> 6) * (tw[i].N >> 5);
;             if (r >= 0 && r < cnt) {
;                 const int nblk = tw[i].N >> 5, kb = r / nblk, nb = r - kb * nblk, k0 = kb * 64, n0 = nb * 32, tid = threadIdx.x & 255;
;                 N = tw[i].N; t.K = tw[i].K; t.mode = tw[i].mode; t.n0 = n0;
;                 t.src = P.in[tw[i].in] + (size_t)(k0 + (tid >> 5)) * tw[i].N + n0 + (tid & 31);
;                 t.dst = (bf16_t*)(P.ws + tw[i].off) + k0 + (tid & 7) * 8;
;             }
;             r -= cnt;
;         }
;     };
;     {
;         const int stride = gridDim.x * 2;
;         int it = blockIdx.x * 2 + hb;
;         TItem cur, nxt; int Nc = 0, Nn = 0; float vn[8];
;         if (blockIdx.x * 2 < total) { lookup(it, nxt, Nn); transpose_load(nxt, Nn, vn); }
;         for (int base = blockIdx.x * 2; base < total; base += stride) {
;             float v[8];
; #pragma unroll
;             for (int i = 0; i < 8; ++i) v[i] = vn[i];
;             cur = nxt; Nc = Nn;
;             if (base + stride < total) { lookup(it + stride, nxt, Nn); transpose_load(nxt, Nn, vn); }
;             transpose_store(cur, v, scr);
;             it += stride;
;         }
;     }
.LBB0_282:
	s_cmpk_lt_u32 s33, 0x58
	s_cbranch_scc1 .Ltq_skip
	v_and_b32_e32 v1, 63, v168
	v_lshrrev_b32_e32 v14, 6, v168
	s_nop 1
	v_readfirstlane_b32 s0, v14
	s_nop 3
	v_lshrrev_b32_e32 v2, 3, v1
	v_and_b32_e32 v3, 7, v1
	v_lshrrev_b32_e32 v4, 2, v2
	v_and_b32_e32 v14, 3, v2
	v_lshl_or_b32 v4, v4, 3, v14
	s_mulk_i32 s0, 0x2100
	s_add_u32 s3, s0, 16
	v_mul_u32_u24_e32 v5, 0x84, v2
	v_lshl_add_u32 v5, v3, 4, v5
	v_add_u32_e32 v5, s3, v5
	v_add_u32_e32 v6, 0x420, v5
	v_add_u32_e32 v7, 0x420, v6
	v_add_u32_e32 v8, 0x420, v7
	v_add_u32_e32 v9, 0x420, v8
	v_add_u32_e32 v10, 0x420, v9
	v_add_u32_e32 v11, 0x420, v10
	v_add_u32_e32 v12, 0x420, v11
	v_mul_u32_u24_e32 v13, 0x420, v3
	v_lshl_add_u32 v13, v2, 2, v13
	v_add_u32_e32 v13, s3, v13
	v_lshlrev_b32_e32 v3, 4, v3
	v_lshrrev_b32_e32 v14, 6, v168
	s_nop 1
	v_readfirstlane_b32 s0, v14
	s_nop 3
	s_sub_u32 s4, s33, 88
	s_lshl_b32 s4, s4, 3
	s_add_u32 s0, s0, s4
	s_mov_b32 s1, s0
	s_movk_i32 s19, 0x2390
	s_cmpk_lt_u32 s1, 0x580
	s_cselect_b32 s19, 0x1b80, s19
	s_add_u32 s19, s19, s1
	s_cmpk_lt_u32 s19, 0x580
	s_cbranch_scc1 .Ltq1_m0
	s_cmpk_lt_u32 s19, 0xb00
	s_cbranch_scc1 .Ltq1_m1
	s_cmpk_lt_u32 s19, 0x1080
	s_cbranch_scc1 .Ltq1_m2
	s_cmpk_lt_u32 s19, 0x1600
	s_cbranch_scc1 .Ltq1_m3
	s_cmpk_lt_u32 s19, 0x1b80
	s_cbranch_scc1 .Ltq1_m4
	s_cmpk_lt_u32 s19, 0x2100
	s_cbranch_scc1 .Ltq1_m5
	s_cmpk_lt_u32 s19, 0x2910
	s_cbranch_scc1 .Ltq1_m6
	s_cmpk_lt_u32 s19, 0x2990
	s_cbranch_scc1 .Ltq1_m7
	s_cmpk_lt_u32 s19, 0x2a90
	s_cbranch_scc1 .Ltq1_m8
	s_cmpk_lt_u32 s19, 0x2b90
	s_cbranch_scc1 .Ltq1_m9
	s_sub_u32 s3, s19, 0x2b90
	v_readlane_b32 s6, v251, 43
	v_readlane_b32 s7, v251, 44
	s_mov_b32 s13, 0x2c00000
	s_mov_b32 s14, 0
	s_branch .Ltq1_c1024_1024

; __device__ __forceinline__ void phase0(const Params& P, unsigned char* smem) {
;     ...
;         for (int base = blockIdx.x * 2; base < total; base += stride) {
;             float v[8];
; #pragma unroll
;             for (int i = 0; i < 8; ++i) v[i] = vn[i];
;             cur = nxt; Nc = Nn;
;             if (base + stride < total) { lookup(it + stride, nxt, Nn); transpose_load(nxt, Nn, vn); }
;             transpose_store(cur, v, scr);
;             it += stride;
;         }
.Ltq_le1:
	s_add_u32 s1, s1, 0x540
	s_cmpk_lt_u32 s1, 0xa00
	s_cbranch_scc0 .Ltq_last0f
	s_movk_i32 s19, 0x2390
	s_cmpk_lt_u32 s1, 0x580
	s_cselect_b32 s19, 0x1b80, s19
	s_add_u32 s19, s19, s1
	s_cmpk_lt_u32 s19, 0x580
	s_cbranch_scc1 .Ltq2_m0
	s_cmpk_lt_u32 s19, 0xb00
	s_cbranch_scc1 .Ltq2_m1
	s_cmpk_lt_u32 s19, 0x1080
	s_cbranch_scc1 .Ltq2_m2
	s_cmpk_lt_u32 s19, 0x1600
	s_cbranch_scc1 .Ltq2_m3
	s_cmpk_lt_u32 s19, 0x1b80
	s_cbranch_scc1 .Ltq2_m4
	s_cmpk_lt_u32 s19, 0x2100
	s_cbranch_scc1 .Ltq2_m5
	s_cmpk_lt_u32 s19, 0x2910
	s_cbranch_scc1 .Ltq2_m6
	s_cmpk_lt_u32 s19, 0x2990
	s_cbranch_scc1 .Ltq2_m7
	s_cmpk_lt_u32 s19, 0x2a90
	s_cbranch_scc1 .Ltq2_m8
	s_cmpk_lt_u32 s19, 0x2b90
	s_cbranch_scc1 .Ltq2_m9
	s_sub_u32 s3, s19, 0x2b90
	v_readlane_b32 s6, v251, 43
	v_readlane_b32 s7, v251, 44
	s_mov_b32 s13, 0x2c00000
	s_mov_b32 s14, 0
	s_branch .Ltq2_c1024_1024

; __device__ __forceinline__ void phase0(const Params& P, unsigned char* smem) {
;     ...
;         for (int base = blockIdx.x * 2; base < total; base += stride) {
;             float v[8];
; #pragma unroll
;             for (int i = 0; i < 8; ++i) v[i] = vn[i];
;             cur = nxt; Nc = Nn;
;             if (base + stride < total) { lookup(it + stride, nxt, Nn); transpose_load(nxt, Nn, vn); }
;             transpose_store(cur, v, scr);
;             it += stride;
;         }
.Ltq_pe1:
.Ltq_loop:
	s_add_u32 s1, s1, 0x540
	s_cmpk_lt_u32 s1, 0xa00
	s_cbranch_scc0 .Ltq_last1
	s_movk_i32 s19, 0x2390
	s_cmpk_lt_u32 s1, 0x580
	s_cselect_b32 s19, 0x1b80, s19
	s_add_u32 s19, s19, s1
	s_cmpk_lt_u32 s19, 0x580
	s_cbranch_scc1 .Ltq3_m0
	s_cmpk_lt_u32 s19, 0xb00
	s_cbranch_scc1 .Ltq3_m1
	s_cmpk_lt_u32 s19, 0x1080
	s_cbranch_scc1 .Ltq3_m2
	s_cmpk_lt_u32 s19, 0x1600
	s_cbranch_scc1 .Ltq3_m3
	s_cmpk_lt_u32 s19, 0x1b80
	s_cbranch_scc1 .Ltq3_m4
	s_cmpk_lt_u32 s19, 0x2100
	s_cbranch_scc1 .Ltq3_m5
	s_cmpk_lt_u32 s19, 0x2910
	s_cbranch_scc1 .Ltq3_m6
	s_cmpk_lt_u32 s19, 0x2990
	s_cbranch_scc1 .Ltq3_m7
	s_cmpk_lt_u32 s19, 0x2a90
	s_cbranch_scc1 .Ltq3_m8
	s_cmpk_lt_u32 s19, 0x2b90
	s_cbranch_scc1 .Ltq3_m9
	s_sub_u32 s3, s19, 0x2b90
	v_readlane_b32 s6, v251, 43
	v_readlane_b32 s7, v251, 44
	s_mov_b32 s13, 0x2c00000
	s_mov_b32 s14, 0
	s_branch .Ltq3_c1024_1024

; __device__ __forceinline__ void phase0(const Params& P, unsigned char* smem) {
;     ...
;         for (int base = blockIdx.x * 2; base < total; base += stride) {
;             float v[8];
; #pragma unroll
;             for (int i = 0; i < 8; ++i) v[i] = vn[i];
;             cur = nxt; Nc = Nn;
;             if (base + stride < total) { lookup(it + stride, nxt, Nn); transpose_load(nxt, Nn, vn); }
;             transpose_store(cur, v, scr);
;             it += stride;
;         }
;     }
.Ltq_pe5:
.Ltq_done:
	s_nop 0
	s_nop 0
	s_nop 0
	s_nop 0
	s_nop 0
	s_nop 0
	s_nop 0
	s_nop 0
	s_nop 0
	s_nop 0
	s_nop 0
	s_nop 0
	s_nop 0
